# attnA epilogue: half-wave exchange (v_permlane32_swap) so each lane stores 8 dwordx4 instead of 16 dwordx2
# speedup vs baseline: 1.0065x; 1.0047x over previous
; __device__ __forceinline__ void subln_store(f32x16 (&o)[4], const float* subg, bf16_t* dst  , int lane) {
;     ...
;     f32x4 sg[4][4];
; #pragma unroll
;     for (int cb = 0; cb < 4; ++cb)
; #pragma unroll
;         for (int g = 0; g < 4; ++g) sg[cb][g] = *(const f32x4*)(subg + 32 * cb + 8 * g + 4 * hi);
; __device__ __forceinline__ void attnA_unit(const P2Ctx& C, int b, int h, int qb) {
;     ...
;     if (comp == 1) {
; #pragma unroll
;         for (int cb = 0; cb < 4; ++cb)
; #pragma unroll
;             for (int r = 0; r < 16; ++r) X2[((qs * 4 + cb) * 16 + r) * 64 + lane] = o[cb][r] * inv;
;     }
;     __syncthreads();
;     if (comp == 0) {
; #pragma unroll
;         for (int cb = 0; cb < 4; ++cb)
; #pragma unroll
;             for (int r = 0; r < 16; ++r) o[cb][r] = o[cb][r] * inv - lam * X2[((qs * 4 + cb) * 16 + r) * 64 + lane];
.LaA_comp0_15:
	v_lshrrev_b32_e32 v242, 5, v219
	v_lshlrev_b32_e32 v242, 4, v242
	v_add_u32_e32 v242, 0x22a00, v242
	ds_read_b128 v[100:103], v242 offset:0
	ds_read_b128 v[104:107], v242 offset:32
	ds_read_b128 v[108:111], v242 offset:64
	ds_read_b128 v[112:115], v242 offset:96
	ds_read_b128 v[116:119], v242 offset:128
	ds_read_b128 v[120:123], v242 offset:160
	ds_read_b128 v[124:127], v242 offset:192
	ds_read_b128 v[128:131], v242 offset:224
	s_waitcnt lgkmcnt(4)
	ds_read_b128 v[132:135], v242 offset:256
	ds_read_b128 v[136:139], v242 offset:288
	ds_read_b128 v[140:143], v242 offset:320
	ds_read_b128 v[144:147], v242 offset:352
	ds_read_b128 v[148:151], v242 offset:384
	ds_read_b128 v[152:155], v242 offset:416
	ds_read_b128 v[156:159], v242 offset:448
	ds_read_b128 v[160:163], v242 offset:480
	s_waitcnt lgkmcnt(6)
	ds_read_b32 v243, v207
	s_nop 7
	s_nop 3
	v_mul_f32_e32 v4, v4, v241
	v_mul_f32_e32 v5, v5, v241
	v_mul_f32_e32 v6, v6, v241
	v_mul_f32_e32 v7, v7, v241
	v_mul_f32_e32 v8, v8, v241
	v_mul_f32_e32 v9, v9, v241
	v_mul_f32_e32 v10, v10, v241
	v_mul_f32_e32 v11, v11, v241
	v_mul_f32_e32 v12, v12, v241
	v_mul_f32_e32 v13, v13, v241
	v_mul_f32_e32 v14, v14, v241
	v_mul_f32_e32 v15, v15, v241
	v_mul_f32_e32 v16, v16, v241
	v_mul_f32_e32 v17, v17, v241
	v_mul_f32_e32 v18, v18, v241
	v_mul_f32_e32 v19, v19, v241
	v_mul_f32_e32 v20, v20, v241
	v_mul_f32_e32 v21, v21, v241
	v_mul_f32_e32 v22, v22, v241
	v_mul_f32_e32 v23, v23, v241
	v_mul_f32_e32 v24, v24, v241
	v_mul_f32_e32 v25, v25, v241
	v_mul_f32_e32 v26, v26, v241
	v_mul_f32_e32 v27, v27, v241
	v_mul_f32_e32 v28, v28, v241
	v_mul_f32_e32 v29, v29, v241
	v_mul_f32_e32 v30, v30, v241
	v_mul_f32_e32 v31, v31, v241
	v_mul_f32_e32 v32, v32, v241
	v_mul_f32_e32 v33, v33, v241
	v_mul_f32_e32 v34, v34, v241
	v_mul_f32_e32 v35, v35, v241
	v_mul_f32_e32 v36, v36, v241
	v_mul_f32_e32 v37, v37, v241
	v_mul_f32_e32 v38, v38, v241
	v_mul_f32_e32 v39, v39, v241
	v_mul_f32_e32 v40, v40, v241
	v_mul_f32_e32 v41, v41, v241
	v_mul_f32_e32 v42, v42, v241
	v_mul_f32_e32 v43, v43, v241
	v_mul_f32_e32 v44, v44, v241
	v_mul_f32_e32 v45, v45, v241
	v_mul_f32_e32 v46, v46, v241
	v_mul_f32_e32 v47, v47, v241
	v_mul_f32_e32 v48, v48, v241
	v_mul_f32_e32 v49, v49, v241
	v_mul_f32_e32 v50, v50, v241
	v_mul_f32_e32 v51, v51, v241
	v_mul_f32_e32 v52, v52, v241
	v_mul_f32_e32 v53, v53, v241
	v_mul_f32_e32 v54, v54, v241
	v_mul_f32_e32 v55, v55, v241
	v_mul_f32_e32 v56, v56, v241
	v_mul_f32_e32 v57, v57, v241
	v_mul_f32_e32 v58, v58, v241
	v_mul_f32_e32 v59, v59, v241
	v_mul_f32_e32 v60, v60, v241
	v_mul_f32_e32 v61, v61, v241
	v_mul_f32_e32 v62, v62, v241
	v_mul_f32_e32 v63, v63, v241
	v_mul_f32_e32 v64, v64, v241
	v_mul_f32_e32 v65, v65, v241
	v_mul_f32_e32 v66, v66, v241
	v_mul_f32_e32 v67, v67, v241
	s_waitcnt lgkmcnt(0)
	s_barrier
	ds_read2st64_b32 v[164:165], v2 offset0:0 offset1:1
	ds_read2st64_b32 v[166:167], v2 offset0:2 offset1:3
	ds_read2st64_b32 v[168:169], v2 offset0:4 offset1:5
	ds_read2st64_b32 v[170:171], v2 offset0:6 offset1:7
	ds_read2st64_b32 v[172:173], v2 offset0:8 offset1:9
	ds_read2st64_b32 v[174:175], v2 offset0:10 offset1:11
	ds_read2st64_b32 v[176:177], v2 offset0:12 offset1:13
	ds_read2st64_b32 v[178:179], v2 offset0:14 offset1:15
	ds_read2st64_b32 v[180:181], v2 offset0:16 offset1:17
	ds_read2st64_b32 v[182:183], v2 offset0:18 offset1:19
	ds_read2st64_b32 v[184:185], v2 offset0:20 offset1:21
	ds_read2st64_b32 v[186:187], v2 offset0:22 offset1:23
	ds_read2st64_b32 v[188:189], v2 offset0:24 offset1:25
	ds_read2st64_b32 v[190:191], v2 offset0:26 offset1:27
	ds_read2st64_b32 v[192:193], v2 offset0:28 offset1:29
	s_waitcnt lgkmcnt(8)
	ds_read2st64_b32 v[194:195], v2 offset0:30 offset1:31
	ds_read2st64_b32 v[68:69], v2 offset0:32 offset1:33
	ds_read2st64_b32 v[70:71], v2 offset0:34 offset1:35
	ds_read2st64_b32 v[72:73], v2 offset0:36 offset1:37
	ds_read2st64_b32 v[74:75], v2 offset0:38 offset1:39
	ds_read2st64_b32 v[76:77], v2 offset0:40 offset1:41
	ds_read2st64_b32 v[78:79], v2 offset0:42 offset1:43
	ds_read2st64_b32 v[80:81], v2 offset0:44 offset1:45
	ds_read2st64_b32 v[82:83], v2 offset0:46 offset1:47
	ds_read2st64_b32 v[84:85], v2 offset0:48 offset1:49
	ds_read2st64_b32 v[86:87], v2 offset0:50 offset1:51
	ds_read2st64_b32 v[88:89], v2 offset0:52 offset1:53
	ds_read2st64_b32 v[90:91], v2 offset0:54 offset1:55
	ds_read2st64_b32 v[92:93], v2 offset0:56 offset1:57
	ds_read2st64_b32 v[94:95], v2 offset0:58 offset1:59
	ds_read2st64_b32 v[96:97], v2 offset0:60 offset1:61
	ds_read2st64_b32 v[98:99], v2 offset0:62 offset1:63
	s_waitcnt lgkmcnt(0)
; __device__ __forceinline__ void subln_store(f32x16 (&o)[4], const float* subg, bf16_t* dst  , int lane) {
;     const int hi = lane >> 5;
;     float ss = 0.f;
; #pragma unroll
;     for (int cb = 0; cb < 4; ++cb)
; #pragma unroll
;         for (int r = 0; r < 16; ++r) ss += o[cb][r] * o[cb][r];
;     ss += __shfl_xor(ss, 32);
;     const float rstd = (1.0f - LAMBDA_INIT) / sqrtf(ss * (1.0f / 128.0f) + EPS);
; __device__ __forceinline__ void attnA_unit(const P2Ctx& C, int b, int h, int qb) {
;     ...
;             for (int r = 0; r < 16; ++r) o[cb][r] = o[cb][r] * inv - lam * X2[((qs * 4 + cb) * 16 + r) * 64 + lane];
	v_fma_f32 v4, -v243, v164, v4
	v_fma_f32 v5, -v243, v165, v5
	v_fma_f32 v6, -v243, v166, v6
	v_fma_f32 v7, -v243, v167, v7
	v_fma_f32 v8, -v243, v168, v8
	v_fma_f32 v9, -v243, v169, v9
	v_fma_f32 v10, -v243, v170, v10
	v_fma_f32 v11, -v243, v171, v11
	v_fma_f32 v12, -v243, v172, v12
	v_fma_f32 v13, -v243, v173, v13
	v_fma_f32 v14, -v243, v174, v14
	v_fma_f32 v15, -v243, v175, v15
	v_fma_f32 v16, -v243, v176, v16
	v_fma_f32 v17, -v243, v177, v17
	v_fma_f32 v18, -v243, v178, v18
	v_fma_f32 v19, -v243, v179, v19
	v_fma_f32 v20, -v243, v180, v20
	v_fma_f32 v21, -v243, v181, v21
	v_fma_f32 v22, -v243, v182, v22
	v_fma_f32 v23, -v243, v183, v23
	v_fma_f32 v24, -v243, v184, v24
	v_fma_f32 v25, -v243, v185, v25
	v_fma_f32 v26, -v243, v186, v26
	v_fma_f32 v27, -v243, v187, v27
	v_fma_f32 v28, -v243, v188, v28
	v_fma_f32 v29, -v243, v189, v29
	v_fma_f32 v30, -v243, v190, v30
	v_fma_f32 v31, -v243, v191, v31
	v_fma_f32 v32, -v243, v192, v32
	v_fma_f32 v33, -v243, v193, v33
	v_fma_f32 v34, -v243, v194, v34
	v_fma_f32 v35, -v243, v195, v35
	v_fma_f32 v36, -v243, v68, v36
	v_fma_f32 v37, -v243, v69, v37
	v_fma_f32 v38, -v243, v70, v38
	v_fma_f32 v39, -v243, v71, v39
	v_fma_f32 v40, -v243, v72, v40
	v_fma_f32 v41, -v243, v73, v41
	v_fma_f32 v42, -v243, v74, v42
	v_fma_f32 v43, -v243, v75, v43
	v_fma_f32 v44, -v243, v76, v44
	v_fma_f32 v45, -v243, v77, v45
	v_fma_f32 v46, -v243, v78, v46
	v_fma_f32 v47, -v243, v79, v47
	v_fma_f32 v48, -v243, v80, v48
	v_fma_f32 v49, -v243, v81, v49
	v_fma_f32 v50, -v243, v82, v50
	v_fma_f32 v51, -v243, v83, v51
	v_fma_f32 v52, -v243, v84, v52
	v_fma_f32 v53, -v243, v85, v53
	v_fma_f32 v54, -v243, v86, v54
	v_fma_f32 v55, -v243, v87, v55
	v_fma_f32 v56, -v243, v88, v56
	v_fma_f32 v57, -v243, v89, v57
	v_fma_f32 v58, -v243, v90, v58
	v_fma_f32 v59, -v243, v91, v59
	v_fma_f32 v60, -v243, v92, v60
	v_fma_f32 v61, -v243, v93, v61
	v_fma_f32 v62, -v243, v94, v62
	v_fma_f32 v63, -v243, v95, v63
	v_fma_f32 v64, -v243, v96, v64
	v_fma_f32 v65, -v243, v97, v65
	v_fma_f32 v66, -v243, v98, v66
	v_fma_f32 v67, -v243, v99, v67
	v_mul_f32_e32 v245, v4, v4
	v_fmac_f32_e32 v245, v5, v5
	v_fmac_f32_e32 v245, v6, v6
	v_fmac_f32_e32 v245, v7, v7
	v_fmac_f32_e32 v245, v8, v8
	v_fmac_f32_e32 v245, v9, v9
	v_fmac_f32_e32 v245, v10, v10
	v_fmac_f32_e32 v245, v11, v11
	v_fmac_f32_e32 v245, v12, v12
	v_fmac_f32_e32 v245, v13, v13
	v_fmac_f32_e32 v245, v14, v14
	v_fmac_f32_e32 v245, v15, v15
	v_fmac_f32_e32 v245, v16, v16
	v_fmac_f32_e32 v245, v17, v17
	v_fmac_f32_e32 v245, v18, v18
	v_fmac_f32_e32 v245, v19, v19
	v_fmac_f32_e32 v245, v20, v20
	v_fmac_f32_e32 v245, v21, v21
	v_fmac_f32_e32 v245, v22, v22
	v_fmac_f32_e32 v245, v23, v23
	v_fmac_f32_e32 v245, v24, v24
	v_fmac_f32_e32 v245, v25, v25
	v_fmac_f32_e32 v245, v26, v26
	v_fmac_f32_e32 v245, v27, v27
	v_fmac_f32_e32 v245, v28, v28
	v_fmac_f32_e32 v245, v29, v29
	v_fmac_f32_e32 v245, v30, v30
	v_fmac_f32_e32 v245, v31, v31
	v_fmac_f32_e32 v245, v32, v32
	v_fmac_f32_e32 v245, v33, v33
	v_fmac_f32_e32 v245, v34, v34
	v_fmac_f32_e32 v245, v35, v35
	v_fmac_f32_e32 v245, v36, v36
	v_fmac_f32_e32 v245, v37, v37
	v_fmac_f32_e32 v245, v38, v38
	v_fmac_f32_e32 v245, v39, v39
	v_fmac_f32_e32 v245, v40, v40
	v_fmac_f32_e32 v245, v41, v41
	v_fmac_f32_e32 v245, v42, v42
	v_fmac_f32_e32 v245, v43, v43
	v_fmac_f32_e32 v245, v44, v44
	v_fmac_f32_e32 v245, v45, v45
	v_fmac_f32_e32 v245, v46, v46
	v_fmac_f32_e32 v245, v47, v47
	v_fmac_f32_e32 v245, v48, v48
	v_fmac_f32_e32 v245, v49, v49
	v_fmac_f32_e32 v245, v50, v50
	v_fmac_f32_e32 v245, v51, v51
	v_fmac_f32_e32 v245, v52, v52
	v_fmac_f32_e32 v245, v53, v53
	v_fmac_f32_e32 v245, v54, v54
	v_fmac_f32_e32 v245, v55, v55
	v_fmac_f32_e32 v245, v56, v56
	v_fmac_f32_e32 v245, v57, v57
	v_fmac_f32_e32 v245, v58, v58
	v_fmac_f32_e32 v245, v59, v59
	v_fmac_f32_e32 v245, v60, v60
	v_fmac_f32_e32 v245, v61, v61
	v_fmac_f32_e32 v245, v62, v62
	v_fmac_f32_e32 v245, v63, v63
	v_fmac_f32_e32 v245, v64, v64
	v_fmac_f32_e32 v245, v65, v65
	v_fmac_f32_e32 v245, v66, v66
	v_fmac_f32_e32 v245, v67, v67
	v_mov_b32_e32 v246, v245
	s_nop 1
	v_permlane32_swap_b32 v246, v245
	v_add_f32_e32 v245, v246, v245
	v_mov_b32_e32 v246, 0x3c000000
	v_fmaak_f32 v245, v245, v246, 0x358637bd
	v_rsq_f32_e32 v245, v245
	s_nop 0
	v_mul_f32_e32 v245, 0x3f4ccccd, v245
	s_lshl_b32 s6, s11, 11
	s_add_i32 s6, s6, s15
	s_lshl_b32 s6, s6, 11
	s_lshl_b32 s7, s81, 1
	s_add_i32 s6, s6, s7
	s_add_u32 s20, s70, s6
	s_addc_u32 s21, s71, 0
	v_and_b32_e32 v242, 31, v219
	v_lshlrev_b32_e32 v242, 11, v242
	v_lshrrev_b32_e32 v243, 5, v219
	v_lshl_add_u32 v242, v243, 4, v242
	s_waitcnt vmcnt(0)
; __device__ __forceinline__ unsigned pk_bf16(float lo, float hi) { f32x2 v = {lo, hi}; bf16x2_t b = __builtin_convertvector(v, bf16x2_t); return __builtin_bit_cast(unsigned, b); }
; __device__ __forceinline__ void subln_store(f32x16 (&o)[4], const float* subg, bf16_t* dst  , int lane) {
;     ...
; #pragma unroll
;     for (int cb = 0; cb < 4; ++cb)
; #pragma unroll
;         for (int g = 0; g < 4; ++g) { const int dv0 = 32 * cb + 8 * g + 4 * hi; const f32x4 s4 = sg[cb][g];
;             u32x2 w; w.x = pk_bf16(o[cb][4 * g + 0] * rstd * s4[0], o[cb][4 * g + 1] * rstd * s4[1]); w.y = pk_bf16(o[cb][4 * g + 2] * rstd * s4[2], o[cb][4 * g + 3] * rstd * s4[3]);
;             *(u32x2*)(dst + dv0) = w; }
	v_mul_f32_e32 v4, v4, v245
	v_mul_f32_e32 v5, v5, v245
	v_mul_f32_e32 v6, v6, v245
	v_mul_f32_e32 v7, v7, v245
	v_mul_f32_e32 v4, v4, v100
	v_mul_f32_e32 v5, v5, v101
	v_mul_f32_e32 v6, v6, v102
	v_mul_f32_e32 v7, v7, v103
	v_mul_f32_e32 v8, v8, v245
	v_mul_f32_e32 v9, v9, v245
	v_mul_f32_e32 v10, v10, v245
	v_mul_f32_e32 v11, v11, v245
	v_mul_f32_e32 v8, v8, v104
	v_mul_f32_e32 v9, v9, v105
	v_mul_f32_e32 v10, v10, v106
	v_mul_f32_e32 v11, v11, v107
	v_cvt_pk_bf16_f32 v68, v4, v5
	v_cvt_pk_bf16_f32 v69, v6, v7
	v_cvt_pk_bf16_f32 v70, v8, v9
	v_cvt_pk_bf16_f32 v71, v10, v11
	s_nop 1
	v_permlane32_swap_b32 v68, v70
	v_permlane32_swap_b32 v69, v71
	global_store_dwordx4 v242, v[68:71], s[20:21] offset:0
	v_mul_f32_e32 v12, v12, v245
	v_mul_f32_e32 v13, v13, v245
	v_mul_f32_e32 v14, v14, v245
	v_mul_f32_e32 v15, v15, v245
	v_mul_f32_e32 v12, v12, v108
	v_mul_f32_e32 v13, v13, v109
	v_mul_f32_e32 v14, v14, v110
	v_mul_f32_e32 v15, v15, v111
	v_mul_f32_e32 v16, v16, v245
	v_mul_f32_e32 v17, v17, v245
	v_mul_f32_e32 v18, v18, v245
	v_mul_f32_e32 v19, v19, v245
	v_mul_f32_e32 v16, v16, v112
	v_mul_f32_e32 v17, v17, v113
	v_mul_f32_e32 v18, v18, v114
	v_mul_f32_e32 v19, v19, v115
	v_cvt_pk_bf16_f32 v72, v12, v13
	v_cvt_pk_bf16_f32 v73, v14, v15
	v_cvt_pk_bf16_f32 v74, v16, v17
	v_cvt_pk_bf16_f32 v75, v18, v19
	s_nop 1
	v_permlane32_swap_b32 v72, v74
	v_permlane32_swap_b32 v73, v75
	global_store_dwordx4 v242, v[72:75], s[20:21] offset:32
	v_mul_f32_e32 v20, v20, v245
	v_mul_f32_e32 v21, v21, v245
	v_mul_f32_e32 v22, v22, v245
	v_mul_f32_e32 v23, v23, v245
	v_mul_f32_e32 v20, v20, v116
	v_mul_f32_e32 v21, v21, v117
	v_mul_f32_e32 v22, v22, v118
	v_mul_f32_e32 v23, v23, v119
	v_mul_f32_e32 v24, v24, v245
	v_mul_f32_e32 v25, v25, v245
	v_mul_f32_e32 v26, v26, v245
	v_mul_f32_e32 v27, v27, v245
	v_mul_f32_e32 v24, v24, v120
	v_mul_f32_e32 v25, v25, v121
	v_mul_f32_e32 v26, v26, v122
	v_mul_f32_e32 v27, v27, v123
	v_cvt_pk_bf16_f32 v68, v20, v21
	v_cvt_pk_bf16_f32 v69, v22, v23
	v_cvt_pk_bf16_f32 v70, v24, v25
	v_cvt_pk_bf16_f32 v71, v26, v27
	s_nop 1
	v_permlane32_swap_b32 v68, v70
	v_permlane32_swap_b32 v69, v71
	global_store_dwordx4 v242, v[68:71], s[20:21] offset:64
	v_mul_f32_e32 v28, v28, v245
	v_mul_f32_e32 v29, v29, v245
	v_mul_f32_e32 v30, v30, v245
	v_mul_f32_e32 v31, v31, v245
	v_mul_f32_e32 v28, v28, v124
	v_mul_f32_e32 v29, v29, v125
	v_mul_f32_e32 v30, v30, v126
	v_mul_f32_e32 v31, v31, v127
	v_mul_f32_e32 v32, v32, v245
	v_mul_f32_e32 v33, v33, v245
	v_mul_f32_e32 v34, v34, v245
	v_mul_f32_e32 v35, v35, v245
	v_mul_f32_e32 v32, v32, v128
	v_mul_f32_e32 v33, v33, v129
	v_mul_f32_e32 v34, v34, v130
	v_mul_f32_e32 v35, v35, v131
	v_cvt_pk_bf16_f32 v72, v28, v29
	v_cvt_pk_bf16_f32 v73, v30, v31
	v_cvt_pk_bf16_f32 v74, v32, v33
	v_cvt_pk_bf16_f32 v75, v34, v35
	s_nop 1
	v_permlane32_swap_b32 v72, v74
	v_permlane32_swap_b32 v73, v75
	global_store_dwordx4 v242, v[72:75], s[20:21] offset:96
	v_mul_f32_e32 v36, v36, v245
	v_mul_f32_e32 v37, v37, v245
	v_mul_f32_e32 v38, v38, v245
	v_mul_f32_e32 v39, v39, v245
	v_mul_f32_e32 v36, v36, v132
	v_mul_f32_e32 v37, v37, v133
	v_mul_f32_e32 v38, v38, v134
	v_mul_f32_e32 v39, v39, v135
	v_mul_f32_e32 v40, v40, v245
	v_mul_f32_e32 v41, v41, v245
	v_mul_f32_e32 v42, v42, v245
	v_mul_f32_e32 v43, v43, v245
	v_mul_f32_e32 v40, v40, v136
	v_mul_f32_e32 v41, v41, v137
	v_mul_f32_e32 v42, v42, v138
	v_mul_f32_e32 v43, v43, v139
	v_cvt_pk_bf16_f32 v68, v36, v37
	v_cvt_pk_bf16_f32 v69, v38, v39
	v_cvt_pk_bf16_f32 v70, v40, v41
	v_cvt_pk_bf16_f32 v71, v42, v43
	s_nop 1
	v_permlane32_swap_b32 v68, v70
	v_permlane32_swap_b32 v69, v71
	global_store_dwordx4 v242, v[68:71], s[20:21] offset:128
	v_mul_f32_e32 v44, v44, v245
	v_mul_f32_e32 v45, v45, v245
	v_mul_f32_e32 v46, v46, v245
	v_mul_f32_e32 v47, v47, v245
	v_mul_f32_e32 v44, v44, v140
	v_mul_f32_e32 v45, v45, v141
	v_mul_f32_e32 v46, v46, v142
	v_mul_f32_e32 v47, v47, v143
	v_mul_f32_e32 v48, v48, v245
	v_mul_f32_e32 v49, v49, v245
	v_mul_f32_e32 v50, v50, v245
	v_mul_f32_e32 v51, v51, v245
	v_mul_f32_e32 v48, v48, v144
	v_mul_f32_e32 v49, v49, v145
	v_mul_f32_e32 v50, v50, v146
	v_mul_f32_e32 v51, v51, v147
	v_cvt_pk_bf16_f32 v72, v44, v45
	v_cvt_pk_bf16_f32 v73, v46, v47
	v_cvt_pk_bf16_f32 v74, v48, v49
	v_cvt_pk_bf16_f32 v75, v50, v51
	s_nop 1
	v_permlane32_swap_b32 v72, v74
	v_permlane32_swap_b32 v73, v75
	global_store_dwordx4 v242, v[72:75], s[20:21] offset:160
	v_mul_f32_e32 v52, v52, v245
	v_mul_f32_e32 v53, v53, v245
	v_mul_f32_e32 v54, v54, v245
	v_mul_f32_e32 v55, v55, v245
	v_mul_f32_e32 v52, v52, v148
	v_mul_f32_e32 v53, v53, v149
	v_mul_f32_e32 v54, v54, v150
	v_mul_f32_e32 v55, v55, v151
	v_mul_f32_e32 v56, v56, v245
	v_mul_f32_e32 v57, v57, v245
	v_mul_f32_e32 v58, v58, v245
	v_mul_f32_e32 v59, v59, v245
	v_mul_f32_e32 v56, v56, v152
	v_mul_f32_e32 v57, v57, v153
	v_mul_f32_e32 v58, v58, v154
	v_mul_f32_e32 v59, v59, v155
	v_cvt_pk_bf16_f32 v68, v52, v53
	v_cvt_pk_bf16_f32 v69, v54, v55
	v_cvt_pk_bf16_f32 v70, v56, v57
	v_cvt_pk_bf16_f32 v71, v58, v59
	s_nop 1
	v_permlane32_swap_b32 v68, v70
	v_permlane32_swap_b32 v69, v71
	global_store_dwordx4 v242, v[68:71], s[20:21] offset:192
	v_mul_f32_e32 v60, v60, v245
	v_mul_f32_e32 v61, v61, v245
	v_mul_f32_e32 v62, v62, v245
	v_mul_f32_e32 v63, v63, v245
	v_mul_f32_e32 v60, v60, v156
	v_mul_f32_e32 v61, v61, v157
	v_mul_f32_e32 v62, v62, v158
	v_mul_f32_e32 v63, v63, v159
	v_mul_f32_e32 v64, v64, v245
	v_mul_f32_e32 v65, v65, v245
	v_mul_f32_e32 v66, v66, v245
	v_mul_f32_e32 v67, v67, v245
	v_mul_f32_e32 v64, v64, v160
	v_mul_f32_e32 v65, v65, v161
	v_mul_f32_e32 v66, v66, v162
	v_mul_f32_e32 v67, v67, v163
	v_cvt_pk_bf16_f32 v72, v60, v61
	v_cvt_pk_bf16_f32 v73, v62, v63
	v_cvt_pk_bf16_f32 v74, v64, v65
	v_cvt_pk_bf16_f32 v75, v66, v67
	s_nop 1
	v_permlane32_swap_b32 v72, v74
	v_permlane32_swap_b32 v73, v75
	global_store_dwordx4 v242, v[72:75], s[20:21] offset:224
